# attention row-max chain reordered (older accumulator first), 15 inline-asm pad s_nop removed
# speedup vs baseline: 1.0087x; 1.0001x over previous
; __device__ __forceinline__ float ex2(float x) { return __builtin_amdgcn_exp2f(x); }
; __device__ __forceinline__ float max3f(float a, float b, float c) { float r; asm("v_max3_f32 %0, %1, %2, %3" : "=v"(r) : "v"(a), "v"(b), "v"(c)); return r; }
; __device__ __forceinline__ float xor32_max(float v) { auto rr = __builtin_amdgcn_permlane32_swap(__float_as_uint(v), __float_as_uint(v), false, false); return fmaxf(__uint_as_float(rr[0]), __uint_as_float(rr[1])); }
; __device__ __forceinline__ void attn_unit(const Params& P, int li, LAS unsigned char* lds, int b, int h, int qb, float lam, float one_m_li) {
;     ...
;             float mx = max3f(p0[0], p1[0], p0[1]);
; #pragma unroll
;             for (int r = 1; r < 15; ++r) mx = max3f(mx, p1[r], p0[r + 1]);
;             mx = max3f(mx, p1[15], mx);
;             const float mt = xor32_max(mx);
;             bool resc; float ra;
;             if (diag) {
;                 resc = true; ra = ex2(m - mt); m = mt;
; #pragma unroll
;                 for (int r = 0; r < 16; ++r) { p0[r] -= mt; p1[r] -= mt; }
;                 const float X = qn * kmx - m + thr; const float ts = floorf(((float)(qpos - 63) - X / sl) * (1.f / 64.f));
;                 const unsigned tsu = ts > 0.f ? (unsigned)ts : 0u; __hip_atomic_fetch_min(ctl, tsu, __ATOMIC_RELAXED, __HIP_MEMORY_SCOPE_WORKGROUP);
;             } else {
;                 resc = __any(mt > AT_DEFER); ra = 1.f;
;                 if (resc) {
;                     const float dl = fmaxf(mt, 0.f); ra = ex2(-dl); m += dl;
; #pragma unroll
;                     for (int r = 0; r < 16; ++r) { p0[r] -= dl; p1[r] -= dl; }
;                 }
.LBB0_419:
	s_nop 0
	s_mov_b64 s[22:23], -1
	s_and_b64 vcc, exec, s[42:43]
	v_max3_f32 v96, v80, v81, v82
	v_max3_f32 v96, v96, v83, v84
	v_max3_f32 v96, v96, v85, v86
	v_max3_f32 v96, v96, v87, v88
	v_max3_f32 v96, v96, v89, v90
	v_max3_f32 v96, v96, v91, v92
	v_max3_f32 v96, v96, v93, v94
	v_max3_f32 v96, v96, v95, v64
	v_max3_f32 v96, v96, v65, v66
	v_max3_f32 v96, v96, v67, v68
	v_max3_f32 v96, v96, v69, v70
	v_max3_f32 v96, v96, v71, v72
	v_max3_f32 v96, v96, v73, v74
	v_max3_f32 v96, v96, v75, v76
	v_max3_f32 v96, v96, v77, v78
	v_max3_f32 v96, v96, v79, v96
	s_nop 0
	v_mov_b32_e32 v97, v96
	s_nop 1
	v_permlane32_swap_b32_e32 v96, v97
	v_max_f32_e32 v97, v97, v97
	v_max_f32_e32 v96, v96, v96
	v_max_f32_e32 v233, v96, v97
	s_cbranch_vccz .LBB0_429
	s_mov_b32 s4, 0x41000000
	v_cmp_lt_f32_e32 vcc, s4, v233
	s_mov_b64 s[22:23], 0
	s_cbranch_vccz .LBB0_437
	v_max_f32_e32 v96, v233, v233
	v_max_f32_e32 v164, 0, v96
	v_exp_f32_e64 v192, -v164
	v_sub_f32_e32 v111, v95, v164
	v_sub_f32_e32 v110, v94, v164
	v_sub_f32_e32 v109, v93, v164
	v_sub_f32_e32 v108, v92, v164
	v_sub_f32_e32 v107, v91, v164
	v_sub_f32_e32 v106, v90, v164
	v_sub_f32_e32 v105, v89, v164
	v_sub_f32_e32 v104, v88, v164
	v_sub_f32_e32 v103, v87, v164
	v_sub_f32_e32 v102, v86, v164
	v_sub_f32_e32 v101, v85, v164
	v_sub_f32_e32 v100, v84, v164
	v_sub_f32_e32 v99, v83, v164
	v_sub_f32_e32 v98, v82, v164
	v_sub_f32_e32 v97, v81, v164
	v_sub_f32_e32 v96, v80, v164
	v_sub_f32_e32 v127, v79, v164
	v_sub_f32_e32 v126, v78, v164
	v_sub_f32_e32 v125, v77, v164
	v_sub_f32_e32 v124, v76, v164
	v_sub_f32_e32 v123, v75, v164
	v_sub_f32_e32 v122, v74, v164
	v_sub_f32_e32 v121, v73, v164
	v_sub_f32_e32 v120, v72, v164
	v_sub_f32_e32 v119, v71, v164
	v_sub_f32_e32 v118, v70, v164
	v_sub_f32_e32 v117, v69, v164
	v_sub_f32_e32 v116, v68, v164
	v_sub_f32_e32 v115, v67, v164
	v_sub_f32_e32 v114, v66, v164
	v_sub_f32_e32 v113, v65, v164
	v_sub_f32_e32 v112, v64, v164
	v_add_f32_e32 v187, v232, v164
	s_mov_b64 s[42:43], -1
	s_andn2_b64 vcc, exec, s[22:23]
	s_cbranch_vccz .LBB0_430
